# LayerNorm passes: removed per-row waits that stalled on store acks (first-iteration waits peeled; LN2 bottom vmcnt(0) -> counted)
# speedup vs baseline: 1.0035x; 1.0035x over previous
; DI void ln_pass(const Params& p, int mode, int l, unsigned char* smem) {
;     ...
;   auto load_mod = [&](int row, float (&msh)[16], float (&msc)[16]) {
;     const float* mb = mod + ((size_t)lm * 40 + batch_of_row(row)) * 6144;
; #pragma unroll
;     for (int i = 0; i < 4; ++i) {
;       const float4 sh = *(const float4*)(mb + shi * 1024 + i * 256 + lane * 4);
;       const float4 sc = *(const float4*)(mb + (shi + 1) * 1024 + i * 256 + lane * 4);
;       msh[i * 4] = sh.x; msh[i * 4 + 1] = sh.y; msh[i * 4 + 2] = sh.z; msh[i * 4 + 3] = sh.w;
;       msc[i * 4] = 1.f + sc.x; msc[i * 4 + 1] = 1.f + sc.y; msc[i * 4 + 2] = 1.f + sc.z; msc[i * 4 + 3] = 1.f + sc.w;
;     }
;   };
;   for (int chunk = blockIdx.x * 8 + w; chunk < TOKP / 32; chunk += gridDim.x * 8) {
;     const int row0 = chunk * 32;
;     float msh[16], msc[16];
;     if (second) load_mod(row0, msh, msc);
;     const float* src0 = (mode == 0) ? p.in[0] + (size_t)row0 * 1024 : p.out + (size_t)row0 * 1024;
;     float4 nx0 = *(const float4*)(src0 + lane * 4), nx1 = *(const float4*)(src0 + 256 + lane * 4);
;     float4 nx2 = *(const float4*)(src0 + 512 + lane * 4), nx3 = *(const float4*)(src0 + 768 + lane * 4);
.LBB0_183:
	v_lshlrev_b32_e32 v40, 5, v83
	v_ashrrev_i32_e32 v8, 6, v83
	v_mad_i64_i32 v[8:9], s[10:11], v8, s30, v[60:61]
	v_ashrrev_i32_e32 v41, 31, v40
	v_readlane_b32 s12, v252, 0
	v_lshl_add_u64 v[20:21], v[8:9], 0, v[56:57]
	v_lshlrev_b64 v[40:41], 12, v[40:41]
	v_readlane_b32 s13, v252, 1
	v_add_co_u32_e32 v32, vcc, 0x1000, v20
	s_nop 0
	v_lshl_add_u64 v[40:41], s[12:13], 0, v[40:41]
	v_lshl_add_u64 v[36:37], v[20:21], 0, s[8:9]
	v_addc_co_u32_e32 v33, vcc, 0, v21, vcc
	v_lshl_add_u64 v[62:63], v[40:41], 0, v[56:57]
	global_load_dwordx4 v[8:11], v[20:21], off
	global_load_dwordx4 v[12:15], v[20:21], off offset:1024
	global_load_dwordx4 v[24:27], v[36:37], off offset:1024
	global_load_dwordx4 v[28:31], v[36:37], off offset:2048
	global_load_dwordx4 v[16:19], v[20:21], off offset:2048
	s_nop 0
	global_load_dwordx4 v[20:23], v[20:21], off offset:3072
	s_nop 0
	global_load_dwordx4 v[32:35], v[32:33], off
	s_nop 0
	global_load_dwordx4 v[36:39], v[36:37], off offset:3072
	s_nop 0
	global_load_dwordx4 v[40:43], v[62:63], off
	global_load_dwordx4 v[44:47], v[62:63], off offset:1024
	global_load_dwordx4 v[48:51], v[62:63], off offset:2048
	global_load_dwordx4 v[52:55], v[62:63], off offset:3072
	s_movk_i32 s34, 0x400
	v_mov_b32_e32 v80, v85
	v_readlane_b32 s14, v252, 2
	v_readlane_b32 s15, v252, 3
	v_readlane_b32 s16, v252, 4
	v_readlane_b32 s17, v252, 5
	v_readlane_b32 s18, v252, 6
	v_readlane_b32 s19, v252, 7
	v_readlane_b32 s20, v252, 8
	v_readlane_b32 s21, v252, 9
	v_readlane_b32 s22, v252, 10
	v_readlane_b32 s23, v252, 11
	v_readlane_b32 s24, v252, 12
	v_readlane_b32 s25, v252, 13
	v_readlane_b32 s26, v252, 14
	v_readlane_b32 s27, v252, 15
	s_waitcnt vmcnt(9)
	v_pk_add_f32 v[64:65], v[24:25], 1.0 op_sel_hi:[1,0]
	v_pk_add_f32 v[66:67], v[26:27], 1.0 op_sel_hi:[1,0]
	s_waitcnt vmcnt(8)
	v_pk_add_f32 v[68:69], v[28:29], 1.0 op_sel_hi:[1,0]
	v_pk_add_f32 v[70:71], v[30:31], 1.0 op_sel_hi:[1,0]
	s_waitcnt vmcnt(5)
	v_pk_add_f32 v[72:73], v[32:33], 1.0 op_sel_hi:[1,0]
	s_waitcnt vmcnt(0)
	v_pk_add_f32 v[74:75], v[36:37], 1.0 op_sel_hi:[1,0]
	v_pk_add_f32 v[76:77], v[38:39], 1.0 op_sel_hi:[1,0]
	v_pk_add_f32 v[78:79], v[34:35], 1.0 op_sel_hi:[1,0]
	s_branch .LBB0_185

; DI void ln_pass(const Params& p, int mode, int l, unsigned char* smem) {
;     ...
;     if (second) {
;       float s = 0.f;
; #pragma unroll
;       for (int i = 0; i < 16; ++i) s += v[i];
;       const float mean = wave_sum(s, lane) * (1.f / 1024.f);
;       float q = 0.f;
; #pragma unroll
;       for (int i = 0; i < 16; ++i) { v[i] -= mean; q += v[i] * v[i]; }
;       const float rstd = rsqrtf(wave_sum(q, lane) * (1.f / 1024.f) + LN_EPS);
; #pragma unroll
;       for (int i = 0; i < 4; ++i) {
; #pragma unroll
;         for (int e = 0; e < 4; ++e) v[i * 4 + e] = v[i * 4 + e] * rstd * msc[i * 4 + e] + msh[i * 4 + e];
;         uint2 o; o.x = pack2(v[i * 4 + 0], v[i * 4 + 1]); o.y = pack2(v[i * 4 + 2], v[i * 4 + 3]);
;         *(uint2*)(H + (size_t)row * 1024 + i * 256 + lane * 4) = o;
;       }
;     ...
;     for (int ri = 0; ri < 32; ++ri) {
;       float v[16];
;       v[0] = nx0.x; v[1] = nx0.y; v[2] = nx0.z; v[3] = nx0.w; v[4] = nx1.x; v[5] = nx1.y; v[6] = nx1.z; v[7] = nx1.w;
;       v[8] = nx2.x; v[9] = nx2.y; v[10] = nx2.z; v[11] = nx2.w; v[12] = nx3.x; v[13] = nx3.y; v[14] = nx3.z; v[15] = nx3.w;
;       {
;         const float* sn = src0 + (size_t)(ri < 31 ? ri + 1 : 31) * 1024;
;         nx0 = *(const float4*)(sn + lane * 4); nx1 = *(const float4*)(sn + 256 + lane * 4);
;         nx2 = *(const float4*)(sn + 512 + lane * 4); nx3 = *(const float4*)(sn + 768 + lane * 4);
;       }
;       __builtin_amdgcn_sched_barrier(0);
;       process(row0 + ri, v, msh, msc);
.LBB0_185:
	s_cmpk_lg_u32 s34, 0x8000
	s_cselect_b32 s4, s34, 0x7c00
	v_lshl_add_u64 v[36:37], s[4:5], 2, v[62:63]
	global_load_dwordx4 v[24:27], v[36:37], off
	global_load_dwordx4 v[28:31], v[36:37], off offset:1024
	global_load_dwordx4 v[32:35], v[36:37], off offset:2048
	s_nop 0
	global_load_dwordx4 v[36:39], v[36:37], off offset:3072
	v_add_f32_e32 v87, 0, v40
	v_add_f32_e32 v87, v41, v87
	v_add_f32_e32 v87, v42, v87
	v_add_f32_e32 v87, v43, v87
	v_add_f32_e32 v87, v44, v87
	v_add_f32_e32 v87, v45, v87
	v_add_f32_e32 v87, v46, v87
	v_add_f32_e32 v87, v47, v87
	v_add_f32_e32 v87, v48, v87
	v_add_f32_e32 v87, v49, v87
	v_add_f32_e32 v87, v50, v87
	v_add_f32_e32 v87, v51, v87
	v_add_f32_e32 v87, v52, v87
	v_add_f32_e32 v87, v53, v87
	v_add_f32_e32 v87, v54, v87
	v_add_f32_e32 v87, v55, v87
	v_ashrrev_i32_e32 v81, 31, v80
	s_nop 0
	v_add_f32_dpp v87, v87, v87 quad_perm:[1,0,3,2] row_mask:0xf bank_mask:0xf bound_ctrl:1
	s_nop 1
	v_add_f32_dpp v87, v87, v87 quad_perm:[2,3,0,1] row_mask:0xf bank_mask:0xf bound_ctrl:1
	s_nop 1
	v_add_f32_dpp v87, v87, v87 row_half_mirror row_mask:0xf bank_mask:0xf bound_ctrl:1
	s_nop 1
	v_add_f32_dpp v87, v87, v87 row_mirror row_mask:0xf bank_mask:0xf bound_ctrl:1
	s_nop 0
	v_readlane_b32 s4, v87, 16
	v_readlane_b32 s12, v87, 48
	v_readlane_b32 s10, v87, 0
	v_readlane_b32 s11, v87, 32
	v_mov_b32_e32 v88, s4
	v_mov_b32_e32 v89, s12
	v_pk_add_f32 v[88:89], s[10:11], v[88:89]
	s_nop 0
	v_add_f32_e32 v87, v88, v89
	v_mul_f32_e32 v88, 0x3a800000, v87
	v_pk_add_f32 v[90:91], v[50:51], v[88:89] op_sel_hi:[1,0] neg_lo:[0,1] neg_hi:[0,1]
	v_pk_add_f32 v[92:93], v[52:53], v[88:89] op_sel_hi:[1,0] neg_lo:[0,1] neg_hi:[0,1]
	v_pk_add_f32 v[94:95], v[54:55], v[88:89] op_sel_hi:[1,0] neg_lo:[0,1] neg_hi:[0,1]
	v_pk_mul_f32 v[50:51], v[90:91], v[90:91]
	v_pk_mul_f32 v[52:53], v[92:93], v[92:93]
	v_pk_mul_f32 v[54:55], v[94:95], v[94:95]
	v_pk_add_f32 v[40:41], v[40:41], v[88:89] op_sel_hi:[1,0] neg_lo:[0,1] neg_hi:[0,1]
	v_pk_add_f32 v[42:43], v[42:43], v[88:89] op_sel_hi:[1,0] neg_lo:[0,1] neg_hi:[0,1]
	v_pk_mul_f32 v[98:99], v[40:41], v[40:41]
	v_pk_mul_f32 v[96:97], v[42:43], v[42:43]
	v_add_f32_e32 v87, v98, v99
	v_pk_add_f32 v[44:45], v[44:45], v[88:89] op_sel_hi:[1,0] neg_lo:[0,1] neg_hi:[0,1]
	v_add_f32_e32 v87, v96, v87
	v_pk_mul_f32 v[102:103], v[44:45], v[44:45]
	v_add_f32_e32 v87, v97, v87
	v_pk_add_f32 v[46:47], v[46:47], v[88:89] op_sel_hi:[1,0] neg_lo:[0,1] neg_hi:[0,1]
	v_add_f32_e32 v87, v102, v87
	v_pk_mul_f32 v[100:101], v[46:47], v[46:47]
	v_add_f32_e32 v87, v103, v87
	v_pk_add_f32 v[88:89], v[48:49], v[88:89] op_sel_hi:[1,0] neg_lo:[0,1] neg_hi:[0,1]
	v_add_f32_e32 v87, v100, v87
	v_pk_mul_f32 v[48:49], v[88:89], v[88:89]
	v_add_f32_e32 v87, v101, v87
	v_add_f32_e32 v48, v48, v87
	v_add_f32_e32 v48, v49, v48
	v_add_f32_e32 v48, v50, v48
	v_add_f32_e32 v48, v51, v48
	v_add_f32_e32 v48, v52, v48
	v_add_f32_e32 v48, v53, v48
	v_add_f32_e32 v48, v54, v48
	v_add_f32_e32 v48, v55, v48
	s_nop 1
	v_add_f32_dpp v48, v48, v48 quad_perm:[1,0,3,2] row_mask:0xf bank_mask:0xf bound_ctrl:1
	s_nop 1
	v_add_f32_dpp v48, v48, v48 quad_perm:[2,3,0,1] row_mask:0xf bank_mask:0xf bound_ctrl:1
	s_nop 1
	v_add_f32_dpp v48, v48, v48 row_half_mirror row_mask:0xf bank_mask:0xf bound_ctrl:1
	s_nop 1
	v_add_f32_dpp v48, v48, v48 row_mirror row_mask:0xf bank_mask:0xf bound_ctrl:1
	s_nop 0
	v_readlane_b32 s4, v48, 16
	v_readlane_b32 s12, v48, 48
	v_readlane_b32 s10, v48, 0
	v_readlane_b32 s11, v48, 32
	v_mov_b32_e32 v48, s4
	v_mov_b32_e32 v49, s12
	v_pk_add_f32 v[48:49], s[10:11], v[48:49]
	s_nop 0
	v_add_f32_e32 v48, v48, v49
	v_fmamk_f32 v48, v48, 0x3a800000, v86
	v_mul_f32_e32 v49, 0x4b800000, v48
	v_cmp_gt_f32_e32 vcc, s31, v48
	s_nop 1
	v_cndmask_b32_e32 v48, v48, v49, vcc
	v_rsq_f32_e32 v50, v48
	v_lshlrev_b64 v[48:49], 11, v[80:81]
	v_lshl_add_u64 v[96:97], v[58:59], 0, v[48:49]
	v_mul_f32_e32 v48, 0x45800000, v50
	v_cndmask_b32_e32 v98, v50, v48, vcc
	v_pk_mul_f32 v[40:41], v[40:41], v[98:99] op_sel_hi:[1,0]
	s_nop 0
	v_pk_fma_f32 v[50:51], v[72:73], v[40:41], v[8:9]
	v_pk_mul_f32 v[40:41], v[42:43], v[98:99] op_sel_hi:[1,0]
	v_pk_mul_f32 v[42:43], v[90:91], v[98:99] op_sel_hi:[1,0]
	v_pk_fma_f32 v[52:53], v[78:79], v[40:41], v[10:11]
	v_cvt_pk_bf16_f32 v40, v50, v51
	v_cvt_pk_bf16_f32 v41, v52, v53
	global_store_dwordx2 v[96:97], v[40:41], off
	v_pk_mul_f32 v[40:41], v[44:45], v[98:99] op_sel_hi:[1,0]
	v_pk_fma_f32 v[42:43], v[70:71], v[42:43], v[18:19]
	v_pk_fma_f32 v[54:55], v[64:65], v[40:41], v[12:13]
	v_pk_mul_f32 v[40:41], v[46:47], v[98:99] op_sel_hi:[1,0]
	v_cvt_pk_bf16_f32 v45, v42, v43
	v_pk_fma_f32 v[48:49], v[66:67], v[40:41], v[14:15]
	v_cvt_pk_bf16_f32 v40, v54, v55
	v_cvt_pk_bf16_f32 v41, v48, v49
	global_store_dwordx2 v[96:97], v[40:41], off offset:512
	v_pk_mul_f32 v[40:41], v[88:89], v[98:99] op_sel_hi:[1,0]
	ds_read_b128 v[88:91], v84 offset:64
	v_pk_fma_f32 v[40:41], v[68:69], v[40:41], v[16:17]
	s_nop 0
	v_cvt_pk_bf16_f32 v44, v40, v41
	global_store_dwordx2 v[96:97], v[44:45], off offset:1024
	v_pk_mul_f32 v[44:45], v[92:93], v[98:99] op_sel_hi:[1,0]
	s_nop 0
	v_pk_fma_f32 v[46:47], v[74:75], v[44:45], v[20:21]
	v_pk_mul_f32 v[44:45], v[94:95], v[98:99] op_sel_hi:[1,0]
	v_cvt_pk_bf16_f32 v92, v46, v47
	v_pk_fma_f32 v[44:45], v[76:77], v[44:45], v[22:23]
	s_nop 0
	v_cvt_pk_bf16_f32 v93, v44, v45
	global_store_dwordx2 v[96:97], v[92:93], off offset:1536
	ds_read_b128 v[92:95], v84 offset:1088
	s_waitcnt lgkmcnt(1)
	v_mul_f32_e32 v87, v89, v51
	v_fmac_f32_e32 v87, v88, v50
	v_fmac_f32_e32 v87, v90, v52
	v_fmac_f32_e32 v87, v91, v53
	s_waitcnt lgkmcnt(0)
; DI void ln_pass(const Params& p, int mode, int l, unsigned char* smem) {
;     ...
;       if (gates) {
;         float g8[8];
; #pragma unroll
;         for (int j = 0; j < 8; ++j) {
;           float s2 = 0.f;
; #pragma unroll
;           for (int i = 0; i < 4; ++i) {
;             const float4 wv = *(const float4*)(wl + j * 1024 + i * 256 + lane * 4);
;             s2 += v[i * 4] * wv.x + v[i * 4 + 1] * wv.y + v[i * 4 + 2] * wv.z + v[i * 4 + 3] * wv.w;
;           }
;           g8[j] = wave_sum(s2, lane) + bif[j];
;         }
	v_mul_f32_e32 v93, v55, v93
	v_fmac_f32_e32 v93, v54, v92
	v_fmac_f32_e32 v93, v48, v94
	v_add_f32_e32 v87, 0, v87
	ds_read_b128 v[88:91], v84 offset:2112
	v_fmac_f32_e32 v93, v49, v95
	v_add_f32_e32 v87, v87, v93
	ds_read_b128 v[92:95], v84 offset:3136
	s_waitcnt lgkmcnt(1)
	v_mul_f32_e32 v89, v41, v89
	v_fmac_f32_e32 v89, v40, v88
	v_fmac_f32_e32 v89, v42, v90
	s_waitcnt lgkmcnt(0)
	v_mul_f32_e32 v88, v47, v93
	v_fmac_f32_e32 v88, v46, v92
	v_fmac_f32_e32 v89, v43, v91
	v_fmac_f32_e32 v88, v44, v94
	v_add_f32_e32 v87, v87, v89
	v_fmac_f32_e32 v88, v45, v95
	v_add_f32_e32 v87, v87, v88
	ds_read_b128 v[88:91], v84 offset:4160
	ds_read_b128 v[92:95], v84 offset:5184
	v_add_f32_dpp v87, v87, v87 quad_perm:[1,0,3,2] row_mask:0xf bank_mask:0xf bound_ctrl:1
	s_waitcnt lgkmcnt(0)
	v_mul_f32_e32 v93, v55, v93
	v_add_f32_dpp v87, v87, v87 quad_perm:[2,3,0,1] row_mask:0xf bank_mask:0xf bound_ctrl:1
	v_fmac_f32_e32 v93, v54, v92
	v_fmac_f32_e32 v93, v48, v94
	v_add_f32_dpp v87, v87, v87 row_half_mirror row_mask:0xf bank_mask:0xf bound_ctrl:1
	v_fmac_f32_e32 v93, v49, v95
	s_nop 0
	v_add_f32_dpp v87, v87, v87 row_mirror row_mask:0xf bank_mask:0xf bound_ctrl:1
	s_nop 0
	v_readlane_b32 s10, v87, 0
	v_readlane_b32 s35, v87, 16
	v_readlane_b32 s12, v87, 32
	v_readlane_b32 s4, v87, 48
	v_mul_f32_e32 v87, v51, v89
	v_fmac_f32_e32 v87, v50, v88
	v_fmac_f32_e32 v87, v52, v90
	v_fmac_f32_e32 v87, v53, v91
	v_add_f32_e32 v87, 0, v87
	ds_read_b128 v[88:91], v84 offset:6208
	v_add_f32_e32 v87, v87, v93
	ds_read_b128 v[92:95], v84 offset:7232
	s_waitcnt lgkmcnt(1)
	v_mul_f32_e32 v89, v41, v89
	v_fmac_f32_e32 v89, v40, v88
	s_waitcnt lgkmcnt(0)
	v_mul_f32_e32 v88, v47, v93
	v_fmac_f32_e32 v89, v42, v90
	v_fmac_f32_e32 v88, v46, v92
	v_fmac_f32_e32 v89, v43, v91
	v_fmac_f32_e32 v88, v44, v94
	v_add_f32_e32 v87, v87, v89
	v_fmac_f32_e32 v88, v45, v95
	v_add_f32_e32 v87, v87, v88
	ds_read_b128 v[88:91], v84 offset:8256
	ds_read_b128 v[92:95], v84 offset:9280
	v_add_f32_dpp v87, v87, v87 quad_perm:[1,0,3,2] row_mask:0xf bank_mask:0xf bound_ctrl:1
	s_waitcnt lgkmcnt(0)
	v_mul_f32_e32 v93, v55, v93
	v_add_f32_dpp v87, v87, v87 quad_perm:[2,3,0,1] row_mask:0xf bank_mask:0xf bound_ctrl:1
	v_fmac_f32_e32 v93, v54, v92
	v_fmac_f32_e32 v93, v48, v94
	v_add_f32_dpp v87, v87, v87 row_half_mirror row_mask:0xf bank_mask:0xf bound_ctrl:1
	v_fmac_f32_e32 v93, v49, v95
	s_nop 0
	v_add_f32_dpp v87, v87, v87 row_mirror row_mask:0xf bank_mask:0xf bound_ctrl:1
	s_nop 0
	v_readlane_b32 s11, v87, 0
	v_readlane_b32 s37, v87, 16
	v_readlane_b32 s13, v87, 32
	v_readlane_b32 s36, v87, 48
	v_mul_f32_e32 v87, v51, v89
	v_fmac_f32_e32 v87, v50, v88
	v_fmac_f32_e32 v87, v52, v90
	v_fmac_f32_e32 v87, v53, v91
	v_add_f32_e32 v87, 0, v87
	ds_read_b128 v[88:91], v84 offset:10304
	v_add_f32_e32 v87, v87, v93
	ds_read_b128 v[92:95], v84 offset:11328
	s_waitcnt lgkmcnt(1)
	v_mul_f32_e32 v89, v41, v89
	v_fmac_f32_e32 v89, v40, v88
	s_waitcnt lgkmcnt(0)
	v_mul_f32_e32 v88, v47, v93
	v_fmac_f32_e32 v89, v42, v90
	v_fmac_f32_e32 v88, v46, v92
	v_fmac_f32_e32 v89, v43, v91
	v_fmac_f32_e32 v88, v44, v94
	v_add_f32_e32 v87, v87, v89
	v_fmac_f32_e32 v88, v45, v95
	v_add_f32_e32 v87, v87, v88
	ds_read_b128 v[88:91], v84 offset:12352
	ds_read_b128 v[92:95], v84 offset:13376
	v_add_f32_dpp v87, v87, v87 quad_perm:[1,0,3,2] row_mask:0xf bank_mask:0xf bound_ctrl:1
	s_waitcnt lgkmcnt(0)
	v_mul_f32_e32 v93, v55, v93
	v_add_f32_dpp v87, v87, v87 quad_perm:[2,3,0,1] row_mask:0xf bank_mask:0xf bound_ctrl:1
	v_fmac_f32_e32 v93, v54, v92
	v_fmac_f32_e32 v93, v48, v94
	v_add_f32_dpp v87, v87, v87 row_half_mirror row_mask:0xf bank_mask:0xf bound_ctrl:1
	v_fmac_f32_e32 v93, v49, v95
	s_nop 0
	v_add_f32_dpp v87, v87, v87 row_mirror row_mask:0xf bank_mask:0xf bound_ctrl:1
	s_nop 0
	v_readlane_b32 s14, v87, 0
	v_readlane_b32 s39, v87, 16
	v_readlane_b32 s16, v87, 32
	v_readlane_b32 s38, v87, 48
	v_mul_f32_e32 v87, v51, v89
	v_fmac_f32_e32 v87, v50, v88
	v_fmac_f32_e32 v87, v52, v90
	v_fmac_f32_e32 v87, v53, v91
	v_add_f32_e32 v87, 0, v87
	ds_read_b128 v[88:91], v84 offset:14400
	v_add_f32_e32 v87, v87, v93
	ds_read_b128 v[92:95], v84 offset:15424
	s_waitcnt lgkmcnt(1)
	v_mul_f32_e32 v89, v41, v89
	v_fmac_f32_e32 v89, v40, v88
	s_waitcnt lgkmcnt(0)
	v_mul_f32_e32 v88, v47, v93
	v_fmac_f32_e32 v89, v42, v90
	v_fmac_f32_e32 v88, v46, v92
	v_fmac_f32_e32 v89, v43, v91
	v_fmac_f32_e32 v88, v44, v94
	v_add_f32_e32 v87, v87, v89
	v_fmac_f32_e32 v88, v45, v95
	v_add_f32_e32 v87, v87, v88
	ds_read_b128 v[88:91], v84 offset:16448
	ds_read_b128 v[92:95], v84 offset:17472
	v_add_f32_dpp v87, v87, v87 quad_perm:[1,0,3,2] row_mask:0xf bank_mask:0xf bound_ctrl:1
	s_waitcnt lgkmcnt(0)
	v_mul_f32_e32 v93, v55, v93
	v_add_f32_dpp v87, v87, v87 quad_perm:[2,3,0,1] row_mask:0xf bank_mask:0xf bound_ctrl:1
	v_fmac_f32_e32 v93, v54, v92
	v_fmac_f32_e32 v93, v48, v94
	v_add_f32_dpp v87, v87, v87 row_half_mirror row_mask:0xf bank_mask:0xf bound_ctrl:1
	v_fmac_f32_e32 v93, v49, v95
	s_nop 0
	v_add_f32_dpp v87, v87, v87 row_mirror row_mask:0xf bank_mask:0xf bound_ctrl:1
	s_nop 0
	v_readlane_b32 s15, v87, 0
	v_readlane_b32 s41, v87, 16
	v_readlane_b32 s17, v87, 32
	v_readlane_b32 s40, v87, 48
	v_mul_f32_e32 v87, v51, v89
	v_fmac_f32_e32 v87, v50, v88
	v_fmac_f32_e32 v87, v52, v90
	v_fmac_f32_e32 v87, v53, v91
	v_add_f32_e32 v87, 0, v87
	ds_read_b128 v[88:91], v84 offset:18496
	v_add_f32_e32 v87, v87, v93
	ds_read_b128 v[92:95], v84 offset:19520
	s_waitcnt lgkmcnt(1)
	v_mul_f32_e32 v89, v41, v89
	v_fmac_f32_e32 v89, v40, v88
	s_waitcnt lgkmcnt(0)
; DI void ln_pass(const Params& p, int mode, int l, unsigned char* smem) {
;     ...
;       if (gates) {
;         float g8[8];
; #pragma unroll
;         for (int j = 0; j < 8; ++j) {
;           float s2 = 0.f;
; #pragma unroll
;           for (int i = 0; i < 4; ++i) {
;             const float4 wv = *(const float4*)(wl + j * 1024 + i * 256 + lane * 4);
;             s2 += v[i * 4] * wv.x + v[i * 4 + 1] * wv.y + v[i * 4 + 2] * wv.z + v[i * 4 + 3] * wv.w;
;           }
;           g8[j] = wave_sum(s2, lane) + bif[j];
;         }
;         if (lane == 0) {
;           *(float4*)(gout + (size_t)row * 8) = make_float4(g8[0], g8[1], g8[2], g8[3]);
;           *(float4*)(gout + (size_t)row * 8 + 4) = make_float4(g8[4], g8[5], g8[6], g8[7]);
;         }
;       }
	v_mul_f32_e32 v88, v47, v93
	v_fmac_f32_e32 v89, v42, v90
	v_fmac_f32_e32 v88, v46, v92
	v_fmac_f32_e32 v89, v43, v91
	v_fmac_f32_e32 v88, v44, v94
	v_add_f32_e32 v87, v87, v89
	v_fmac_f32_e32 v88, v45, v95
	v_add_f32_e32 v87, v87, v88
	ds_read_b128 v[88:91], v84 offset:20544
	ds_read_b128 v[92:95], v84 offset:21568
	v_add_f32_dpp v87, v87, v87 quad_perm:[1,0,3,2] row_mask:0xf bank_mask:0xf bound_ctrl:1
	s_waitcnt lgkmcnt(0)
	v_mul_f32_e32 v93, v55, v93
	v_add_f32_dpp v87, v87, v87 quad_perm:[2,3,0,1] row_mask:0xf bank_mask:0xf bound_ctrl:1
	v_fmac_f32_e32 v93, v54, v92
	v_fmac_f32_e32 v93, v48, v94
	v_add_f32_dpp v87, v87, v87 row_half_mirror row_mask:0xf bank_mask:0xf bound_ctrl:1
	v_fmac_f32_e32 v93, v49, v95
	s_nop 0
	v_add_f32_dpp v87, v87, v87 row_mirror row_mask:0xf bank_mask:0xf bound_ctrl:1
	s_nop 0
	v_readlane_b32 s18, v87, 0
	v_readlane_b32 s43, v87, 16
	v_readlane_b32 s20, v87, 32
	v_readlane_b32 s42, v87, 48
	v_mul_f32_e32 v87, v51, v89
	v_fmac_f32_e32 v87, v50, v88
	v_fmac_f32_e32 v87, v52, v90
	v_fmac_f32_e32 v87, v53, v91
	v_add_f32_e32 v87, 0, v87
	ds_read_b128 v[88:91], v84 offset:22592
	v_add_f32_e32 v87, v87, v93
	ds_read_b128 v[92:95], v84 offset:23616
	s_waitcnt lgkmcnt(1)
	v_mul_f32_e32 v89, v41, v89
	v_fmac_f32_e32 v89, v40, v88
	s_waitcnt lgkmcnt(0)
	v_mul_f32_e32 v88, v47, v93
	v_fmac_f32_e32 v89, v42, v90
	v_fmac_f32_e32 v88, v46, v92
	v_fmac_f32_e32 v89, v43, v91
	v_fmac_f32_e32 v88, v44, v94
	v_add_f32_e32 v87, v87, v89
	v_fmac_f32_e32 v88, v45, v95
	v_add_f32_e32 v87, v87, v88
	ds_read_b128 v[88:91], v84 offset:24640
	ds_read_b128 v[92:95], v84 offset:25664
	v_add_f32_dpp v87, v87, v87 quad_perm:[1,0,3,2] row_mask:0xf bank_mask:0xf bound_ctrl:1
	s_waitcnt lgkmcnt(0)
	v_mul_f32_e32 v93, v55, v93
	v_add_f32_dpp v87, v87, v87 quad_perm:[2,3,0,1] row_mask:0xf bank_mask:0xf bound_ctrl:1
	v_fmac_f32_e32 v93, v54, v92
	v_fmac_f32_e32 v93, v48, v94
	v_add_f32_dpp v87, v87, v87 row_half_mirror row_mask:0xf bank_mask:0xf bound_ctrl:1
	v_fmac_f32_e32 v93, v49, v95
	s_nop 0
	v_add_f32_dpp v87, v87, v87 row_mirror row_mask:0xf bank_mask:0xf bound_ctrl:1
	s_nop 0
	v_readlane_b32 s19, v87, 0
	v_readlane_b32 s45, v87, 16
	v_readlane_b32 s21, v87, 32
	v_readlane_b32 s44, v87, 48
	v_mul_f32_e32 v87, v51, v89
	v_fmac_f32_e32 v87, v50, v88
	v_fmac_f32_e32 v87, v52, v90
	v_fmac_f32_e32 v87, v53, v91
	v_add_f32_e32 v87, 0, v87
	ds_read_b128 v[88:91], v84 offset:26688
	v_add_f32_e32 v87, v87, v93
	ds_read_b128 v[92:95], v84 offset:27712
	s_waitcnt lgkmcnt(1)
	v_mul_f32_e32 v89, v41, v89
	v_fmac_f32_e32 v89, v40, v88
	s_waitcnt lgkmcnt(0)
	v_mul_f32_e32 v88, v47, v93
	v_fmac_f32_e32 v89, v42, v90
	v_fmac_f32_e32 v88, v46, v92
	v_fmac_f32_e32 v89, v43, v91
	v_fmac_f32_e32 v88, v44, v94
	v_add_f32_e32 v87, v87, v89
	v_fmac_f32_e32 v88, v45, v95
	v_add_f32_e32 v87, v87, v88
	ds_read_b128 v[88:91], v84 offset:28736
	ds_read_b128 v[92:95], v84 offset:29760
	v_add_f32_dpp v87, v87, v87 quad_perm:[1,0,3,2] row_mask:0xf bank_mask:0xf bound_ctrl:1
	s_waitcnt lgkmcnt(1)
	v_mul_f32_e32 v51, v51, v89
	v_add_f32_dpp v87, v87, v87 quad_perm:[2,3,0,1] row_mask:0xf bank_mask:0xf bound_ctrl:1
	v_fmac_f32_e32 v51, v50, v88
	v_fmac_f32_e32 v51, v52, v90
	v_add_f32_dpp v87, v87, v87 row_half_mirror row_mask:0xf bank_mask:0xf bound_ctrl:1
	v_fmac_f32_e32 v51, v53, v91
	s_waitcnt lgkmcnt(0)
	v_mul_f32_e32 v55, v55, v93
	v_add_f32_dpp v87, v87, v87 row_mirror row_mask:0xf bank_mask:0xf bound_ctrl:1
	ds_read_b128 v[88:91], v84 offset:31808
	v_readlane_b32 s22, v87, 0
	v_readlane_b32 s47, v87, 16
	v_readlane_b32 s24, v87, 32
	v_readlane_b32 s46, v87, 48
	v_add_f32_e32 v87, 0, v51
	ds_read_b128 v[50:53], v84 offset:30784
	v_fmac_f32_e32 v55, v54, v92
	v_fmac_f32_e32 v55, v48, v94
	v_fmac_f32_e32 v55, v49, v95
	v_add_f32_e32 v48, v87, v55
	s_waitcnt lgkmcnt(0)
	v_mul_f32_e32 v41, v41, v51
	v_fmac_f32_e32 v41, v40, v50
	v_fmac_f32_e32 v41, v42, v52
	v_fmac_f32_e32 v41, v43, v53
	v_add_f32_e32 v40, v48, v41
	v_mul_f32_e32 v41, v47, v89
	v_fmac_f32_e32 v41, v46, v88
	v_fmac_f32_e32 v41, v44, v90
	v_fmac_f32_e32 v41, v45, v91
	v_add_f32_e32 v40, v40, v41
	s_nop 1
	v_add_f32_dpp v40, v40, v40 quad_perm:[1,0,3,2] row_mask:0xf bank_mask:0xf bound_ctrl:1
	s_nop 1
	v_add_f32_dpp v40, v40, v40 quad_perm:[2,3,0,1] row_mask:0xf bank_mask:0xf bound_ctrl:1
	s_nop 1
	v_add_f32_dpp v40, v40, v40 row_half_mirror row_mask:0xf bank_mask:0xf bound_ctrl:1
	s_nop 1
	v_add_f32_dpp v40, v40, v40 row_mirror row_mask:0xf bank_mask:0xf bound_ctrl:1
	s_nop 0
	v_readlane_b32 s23, v40, 0
	v_readlane_b32 s49, v40, 16
	v_readlane_b32 s25, v40, 32
	v_readlane_b32 s48, v40, 48
	s_and_saveexec_b64 s[26:27], s[0:1]
	s_cbranch_execz .LBB0_184
	v_mov_b32_e32 v42, s39
	v_mov_b32_e32 v43, s41
	v_mov_b32_e32 v52, s38
	v_mov_b32_e32 v53, s40
	v_mov_b32_e32 v40, s35
	v_mov_b32_e32 v41, s37
	v_mov_b32_e32 v54, s4
	v_mov_b32_e32 v55, s36
	v_pk_add_f32 v[40:41], s[10:11], v[40:41]
	v_pk_add_f32 v[54:55], s[12:13], v[54:55]
	v_pk_add_f32 v[42:43], s[14:15], v[42:43]
	v_pk_add_f32 v[52:53], s[16:17], v[52:53]
	v_lshlrev_b64 v[88:89], 5, v[80:81]
	v_pk_add_f32 v[40:41], v[40:41], v[54:55]
	v_pk_add_f32 v[42:43], v[42:43], v[52:53]
	v_mov_b32_e32 v48, s43
	v_mov_b32_e32 v49, s45
	v_mov_b32_e32 v50, s42
	v_mov_b32_e32 v51, s44
	v_lshl_add_u64 v[88:89], s[96:97], 0, v[88:89]
	v_pk_add_f32 v[40:41], v[4:5], v[40:41]
	v_pk_add_f32 v[42:43], v[6:7], v[42:43]
	v_mov_b32_e32 v44, s47
	v_mov_b32_e32 v45, s49
	v_mov_b32_e32 v46, s46
	v_mov_b32_e32 v47, s48
	global_store_dwordx4 v[88:89], v[40:43], off
	s_nop 1
	v_pk_add_f32 v[40:41], s[18:19], v[48:49]
	v_pk_add_f32 v[42:43], s[20:21], v[50:51]
	s_nop 0
	v_pk_add_f32 v[40:41], v[40:41], v[42:43]
	v_pk_add_f32 v[42:43], s[22:23], v[44:45]
	v_pk_add_f32 v[44:45], s[24:25], v[46:47]
	v_pk_add_f32 v[40:41], v[0:1], v[40:41]
	v_pk_add_f32 v[42:43], v[42:43], v[44:45]
	s_nop 0
	v_pk_add_f32 v[42:43], v[2:3], v[42:43]
	global_store_dwordx4 v[88:89], v[40:43], off offset:16
	s_branch .LBB0_184

; DI void ln_pass(const Params& p, int mode, int l, unsigned char* smem) {
;     ...
;   auto load_mod = [&](int row, float (&msh)[16], float (&msc)[16]) {
;     const float* mb = mod + ((size_t)lm * 40 + batch_of_row(row)) * 6144;
; #pragma unroll
;     for (int i = 0; i < 4; ++i) {
;       const float4 sh = *(const float4*)(mb + shi * 1024 + i * 256 + lane * 4);
;       const float4 sc = *(const float4*)(mb + (shi + 1) * 1024 + i * 256 + lane * 4);
;       msh[i * 4] = sh.x; msh[i * 4 + 1] = sh.y; msh[i * 4 + 2] = sh.z; msh[i * 4 + 3] = sh.w;
;       msc[i * 4] = 1.f + sc.x; msc[i * 4 + 1] = 1.f + sc.y; msc[i * 4 + 2] = 1.f + sc.z; msc[i * 4 + 3] = 1.f + sc.w;
;     }
;   };
;   for (int chunk = blockIdx.x * 8 + w; chunk < TOKP / 32; chunk += gridDim.x * 8) {
;     const int row0 = chunk * 32;
;     float msh[16], msc[16];
;     if (second) load_mod(row0, msh, msc);
;     const float* src0 = (mode == 0) ? p.in[0] + (size_t)row0 * 1024 : p.out + (size_t)row0 * 1024;
;     float4 nx0 = *(const float4*)(src0 + lane * 4), nx1 = *(const float4*)(src0 + 256 + lane * 4);
;     float4 nx2 = *(const float4*)(src0 + 512 + lane * 4), nx3 = *(const float4*)(src0 + 768 + lane * 4);
.LBB0_769:
	v_ashrrev_i32_e32 v32, 6, v110
	v_ashrrev_i32_e32 v33, 31, v32
	v_lshl_add_u64 v[32:33], v[32:33], 0, s[14:15]
	v_mov_b64_e32 v[34:35], s[20:21]
	v_mad_u64_u32 v[34:35], s[2:3], v32, s86, v[34:35]
	v_mad_i32_i24 v35, v33, s86, v35
	v_lshlrev_b32_e32 v178, 2, v111
	v_lshl_add_u64 v[52:53], v[34:35], 0, v[178:179]
	s_mov_b64 s[2:3], 0x1000
	v_lshl_add_u64 v[54:55], v[52:53], 0, s[2:3]
	global_load_dwordx4 v[32:35], v[52:53], off offset:2048
	global_load_dwordx4 v[48:51], v[54:55], off offset:2048
	global_load_dwordx4 v[36:39], v[52:53], off offset:3072
	global_load_dwordx4 v[40:43], v[54:55], off offset:3072
	v_lshlrev_b32_e32 v44, 5, v110
	v_ashrrev_i32_e32 v45, 31, v44
	v_readlane_b32 s36, v253, 43
	s_movk_i32 s2, 0x1000
	v_readlane_b32 s48, v253, 55
	v_readlane_b32 s49, v253, 56
	s_movk_i32 s8, 0x400
	v_mov_b32_e32 v100, v112
	s_mov_b32 s11, 0x800000
	v_readlane_b32 s37, v253, 44
	v_readlane_b32 s38, v253, 45
	v_readlane_b32 s39, v253, 46
	v_readlane_b32 s40, v253, 47
	v_readlane_b32 s41, v253, 48
	v_readlane_b32 s42, v253, 49
	v_readlane_b32 s43, v253, 50
	v_readlane_b32 s44, v253, 51
	v_readlane_b32 s45, v253, 52
	v_readlane_b32 s46, v253, 53
	v_readlane_b32 s47, v253, 54
	v_readlane_b32 s50, v253, 57
	v_readlane_b32 s51, v253, 58
	s_waitcnt vmcnt(2)
	v_pk_add_f32 v[82:83], v[50:51], 1.0 op_sel_hi:[1,0]
	s_waitcnt vmcnt(0)
	v_pk_add_f32 v[84:85], v[40:41], 1.0 op_sel_hi:[1,0]
	v_lshlrev_b64 v[40:41], 12, v[44:45]
	v_add_co_u32_e64 v44, s[2:3], s2, v52
	v_lshl_add_u64 v[40:41], s[48:49], 0, v[40:41]
	s_nop 0
	v_addc_co_u32_e64 v45, s[2:3], 0, v53, s[2:3]
	v_pk_add_f32 v[86:87], v[42:43], 1.0 op_sel_hi:[1,0]
	v_lshl_add_u64 v[88:89], v[40:41], 0, v[178:179]
	global_load_dwordx4 v[40:43], v[52:53], off
	global_load_dwordx4 v[64:67], v[88:89], off
	v_pk_add_f32 v[98:99], v[48:49], 1.0 op_sel_hi:[1,0]
	global_load_dwordx4 v[44:47], v[44:45], off
	s_waitcnt vmcnt(0)
	v_pk_add_f32 v[90:91], v[44:45], 1.0 op_sel_hi:[1,0]
	v_pk_add_f32 v[92:93], v[46:47], 1.0 op_sel_hi:[1,0]
	global_load_dwordx4 v[44:47], v[52:53], off offset:1024
	s_nop 0
	global_load_dwordx4 v[50:53], v[54:55], off offset:1024
	global_load_dwordx4 v[68:71], v[88:89], off offset:1024
	global_load_dwordx4 v[72:75], v[88:89], off offset:2048
	global_load_dwordx4 v[76:79], v[88:89], off offset:3072
	s_waitcnt vmcnt(0)
	v_pk_add_f32 v[94:95], v[50:51], 1.0 op_sel_hi:[1,0]
	v_pk_add_f32 v[96:97], v[52:53], 1.0 op_sel_hi:[1,0]
	s_branch .LBB0_771

; DI void ln_pass(const Params& p, int mode, int l, unsigned char* smem) {
;     ...
;     if (first) {
;       float s = 0.f;
; #pragma unroll
;       for (int i = 0; i < 16; ++i) s += v[i];
;       const float mean = wave_sum(s, lane) * (1.f / 1024.f);
;       float q = 0.f;
; #pragma unroll
;       for (int i = 0; i < 16; ++i) { v[i] -= mean; q += v[i] * v[i]; }
;       const float rstd = rsqrtf(wave_sum(q, lane) * (1.f / 1024.f) + LN_EPS);
; #pragma unroll
;       for (int i = 0; i < 4; ++i) {
; #pragma unroll
;         for (int e = 0; e < 4; ++e) v[i * 4 + e] = v[i * 4 + e] * rstd * lg[i * 4 + e] + lb[i * 4 + e];
;         if (write_x) *(float4*)(xr + i * 256 + lane * 4) = make_float4(v[i * 4 + 0], v[i * 4 + 1], v[i * 4 + 2], v[i * 4 + 3]);
;       }
;       if (!write_x && lane == 0) *(float2*)(stats + (size_t)row * 2) = make_float2(mean, rstd);
;     ...
;     for (int ri = 0; ri < 32; ++ri) {
;       float v[16];
;       v[0] = nx0.x; v[1] = nx0.y; v[2] = nx0.z; v[3] = nx0.w; v[4] = nx1.x; v[5] = nx1.y; v[6] = nx1.z; v[7] = nx1.w;
;       v[8] = nx2.x; v[9] = nx2.y; v[10] = nx2.z; v[11] = nx2.w; v[12] = nx3.x; v[13] = nx3.y; v[14] = nx3.z; v[15] = nx3.w;
;       {
;         const float* sn = src0 + (size_t)(ri < 31 ? ri + 1 : 31) * 1024;
;         nx0 = *(const float4*)(sn + lane * 4); nx1 = *(const float4*)(sn + 256 + lane * 4);
;         nx2 = *(const float4*)(sn + 512 + lane * 4); nx3 = *(const float4*)(sn + 768 + lane * 4);
;       }
;       __builtin_amdgcn_sched_barrier(0);
;       process(row0 + ri, v, msh, msc);
.LBB0_771:
	s_cmpk_lg_u32 s8, 0x8000
	s_cselect_b32 s82, s8, 0x7c00
	v_lshl_add_u64 v[56:57], s[82:83], 2, v[88:89]
	global_load_dwordx4 v[48:51], v[56:57], off offset:3072
	global_load_dwordx4 v[52:55], v[56:57], off offset:2048
	global_load_dwordx4 v[60:63], v[56:57], off
	s_nop 0
	global_load_dwordx4 v[56:59], v[56:57], off offset:1024
	v_add_f32_e32 v102, 0, v64
	v_add_f32_e32 v102, v65, v102
	v_add_f32_e32 v102, v66, v102
	v_add_f32_e32 v102, v67, v102
	v_add_f32_e32 v102, v68, v102
	v_add_f32_e32 v102, v69, v102
	v_add_f32_e32 v102, v70, v102
	v_add_f32_e32 v102, v71, v102
	v_add_f32_e32 v102, v72, v102
	v_add_f32_e32 v102, v73, v102
	v_add_f32_e32 v102, v74, v102
	v_add_f32_e32 v102, v75, v102
	v_add_f32_e32 v102, v76, v102
	v_add_f32_e32 v102, v77, v102
	v_add_f32_e32 v102, v78, v102
	v_add_f32_e32 v102, v79, v102
	v_ashrrev_i32_e32 v101, 31, v100
	s_nop 0
	v_add_f32_dpp v102, v102, v102 quad_perm:[1,0,3,2] row_mask:0xf bank_mask:0xf bound_ctrl:1
	s_nop 1
	v_add_f32_dpp v102, v102, v102 quad_perm:[2,3,0,1] row_mask:0xf bank_mask:0xf bound_ctrl:1
	s_nop 1
	v_add_f32_dpp v102, v102, v102 row_half_mirror row_mask:0xf bank_mask:0xf bound_ctrl:1
	s_nop 1
	v_add_f32_dpp v102, v102, v102 row_mirror row_mask:0xf bank_mask:0xf bound_ctrl:1
	s_nop 0
	v_readlane_b32 s9, v102, 16
	v_readlane_b32 s10, v102, 48
	v_readlane_b32 s2, v102, 0
	v_readlane_b32 s3, v102, 32
	v_mov_b32_e32 v102, s9
	v_mov_b32_e32 v103, s10
	v_pk_add_f32 v[102:103], s[2:3], v[102:103]
	s_nop 0
	v_add_f32_e32 v102, v102, v103
	v_mul_f32_e32 v106, 0x3a800000, v102
	v_pk_add_f32 v[102:103], v[66:67], v[106:107] op_sel_hi:[1,0] neg_lo:[0,1] neg_hi:[0,1]
	v_pk_add_f32 v[66:67], v[76:77], v[106:107] op_sel_hi:[1,0] neg_lo:[0,1] neg_hi:[0,1]
	v_pk_add_f32 v[76:77], v[68:69], v[106:107] op_sel_hi:[1,0] neg_lo:[0,1] neg_hi:[0,1]
	v_pk_add_f32 v[68:69], v[72:73], v[106:107] op_sel_hi:[1,0] neg_lo:[0,1] neg_hi:[0,1]
	v_pk_add_f32 v[104:105], v[64:65], v[106:107] op_sel_hi:[1,0] neg_lo:[0,1] neg_hi:[0,1]
	v_pk_add_f32 v[64:65], v[78:79], v[106:107] op_sel_hi:[1,0] neg_lo:[0,1] neg_hi:[0,1]
	v_pk_add_f32 v[74:75], v[74:75], v[106:107] op_sel_hi:[1,0] neg_lo:[0,1] neg_hi:[0,1]
	v_pk_add_f32 v[70:71], v[70:71], v[106:107] op_sel_hi:[1,0] neg_lo:[0,1] neg_hi:[0,1]
	v_pk_mul_f32 v[72:73], v[68:69], v[68:69]
	v_pk_mul_f32 v[114:115], v[102:103], v[102:103]
	v_pk_mul_f32 v[116:117], v[104:105], v[104:105]
	v_pk_mul_f32 v[78:79], v[64:65], v[64:65]
	v_pk_mul_f32 v[118:119], v[66:67], v[66:67]
	v_pk_mul_f32 v[120:121], v[74:75], v[74:75]
	v_pk_mul_f32 v[122:123], v[70:71], v[70:71]
	v_pk_mul_f32 v[124:125], v[76:77], v[76:77]
	v_add_f32_e32 v107, v116, v117
	v_add_f32_e32 v107, v114, v107
	v_add_f32_e32 v107, v115, v107
	v_add_f32_e32 v107, v124, v107
	v_add_f32_e32 v107, v125, v107
	v_add_f32_e32 v107, v122, v107
	v_add_f32_e32 v107, v123, v107
	v_add_f32_e32 v72, v72, v107
	v_add_f32_e32 v72, v73, v72
	v_add_f32_e32 v72, v120, v72
	v_add_f32_e32 v72, v121, v72
	v_add_f32_e32 v72, v118, v72
	v_add_f32_e32 v72, v119, v72
	v_add_f32_e32 v72, v78, v72
	v_add_f32_e32 v72, v79, v72
	s_nop 1
	v_add_f32_dpp v72, v72, v72 quad_perm:[1,0,3,2] row_mask:0xf bank_mask:0xf bound_ctrl:1
	s_nop 1
	v_add_f32_dpp v72, v72, v72 quad_perm:[2,3,0,1] row_mask:0xf bank_mask:0xf bound_ctrl:1
	s_nop 1
	v_add_f32_dpp v72, v72, v72 row_half_mirror row_mask:0xf bank_mask:0xf bound_ctrl:1
	s_nop 1
	v_add_f32_dpp v72, v72, v72 row_mirror row_mask:0xf bank_mask:0xf bound_ctrl:1
	s_nop 0
	v_readlane_b32 s9, v72, 16
	v_readlane_b32 s10, v72, 48
	v_readlane_b32 s2, v72, 0
	v_readlane_b32 s3, v72, 32
	v_mov_b32_e32 v72, s9
	v_mov_b32_e32 v73, s10
	v_pk_add_f32 v[72:73], s[2:3], v[72:73]
	s_nop 0
	v_add_f32_e32 v72, v72, v73
	v_fmamk_f32 v72, v72, 0x3a800000, v217
	v_mul_f32_e32 v73, 0x4b800000, v72
	v_cmp_gt_f32_e64 s[2:3], s11, v72
	s_nop 1
	v_cndmask_b32_e64 v72, v72, v73, s[2:3]
	v_rsq_f32_e32 v72, v72
	s_nop 0
	v_mul_f32_e32 v73, 0x45800000, v72
	v_cndmask_b32_e64 v72, v72, v73, s[2:3]
	s_and_saveexec_b64 s[2:3], vcc
	s_cbranch_execz .LBB0_770
	v_lshl_add_u64 v[78:79], v[100:101], 3, s[80:81]
	v_mov_b32_e32 v107, v72
	global_store_dwordx2 v[78:79], v[106:107], off
	s_branch .LBB0_770

; DI void ln_pass(const Params& p, int mode, int l, unsigned char* smem) {
;     ...
;   for (int chunk = blockIdx.x * 8 + w; chunk < TOKP / 32; chunk += gridDim.x * 8) {
;     const int row0 = chunk * 32;
;     float msh[16], msc[16];
;     if (second) load_mod(row0, msh, msc);
;     const float* src0 = (mode == 0) ? p.in[0] + (size_t)row0 * 1024 : p.out + (size_t)row0 * 1024;
;     float4 nx0 = *(const float4*)(src0 + lane * 4), nx1 = *(const float4*)(src0 + 256 + lane * 4);
;     float4 nx2 = *(const float4*)(src0 + 512 + lane * 4), nx3 = *(const float4*)(src0 + 768 + lane * 4);
.LBB0_912:
	v_lshlrev_b32_e32 v56, 5, v118
	v_ashrrev_i32_e32 v57, 31, v56
	v_readlane_b32 s12, v253, 43
	v_lshlrev_b64 v[56:57], 12, v[56:57]
	v_readlane_b32 s24, v253, 55
	v_readlane_b32 s25, v253, 56
	s_movk_i32 s29, 0x400
	v_mov_b32_e32 v110, v121
	v_lshl_add_u64 v[56:57], s[24:25], 0, v[56:57]
	v_lshl_add_u64 v[108:109], v[56:57], 0, v[178:179]
	global_load_dwordx4 v[72:75], v[108:109], off
	global_load_dwordx4 v[76:79], v[108:109], off offset:1024
	global_load_dwordx4 v[80:83], v[108:109], off offset:2048
	global_load_dwordx4 v[84:87], v[108:109], off offset:3072
	v_readlane_b32 s13, v253, 44
	v_readlane_b32 s14, v253, 45
	v_readlane_b32 s15, v253, 46
	v_readlane_b32 s16, v253, 47
	v_readlane_b32 s17, v253, 48
	v_readlane_b32 s18, v253, 49
	v_readlane_b32 s19, v253, 50
	v_readlane_b32 s20, v253, 51
	v_readlane_b32 s21, v253, 52
	v_readlane_b32 s22, v253, 53
	v_readlane_b32 s23, v253, 54
	v_readlane_b32 s26, v253, 57
	v_readlane_b32 s27, v253, 58
	s_waitcnt vmcnt(0)
	s_branch .LBB0_915

; DI void ln_pass(const Params& p, int mode, int l, unsigned char* smem) {
;     ...
;     if (first) {
;       float s = 0.f;
; #pragma unroll
;       for (int i = 0; i < 16; ++i) s += v[i];
;       const float mean = wave_sum(s, lane) * (1.f / 1024.f);
;       float q = 0.f;
; #pragma unroll
;       for (int i = 0; i < 16; ++i) { v[i] -= mean; q += v[i] * v[i]; }
;       const float rstd = rsqrtf(wave_sum(q, lane) * (1.f / 1024.f) + LN_EPS);
; #pragma unroll
;       for (int i = 0; i < 4; ++i) {
; #pragma unroll
;         for (int e = 0; e < 4; ++e) v[i * 4 + e] = v[i * 4 + e] * rstd * lg[i * 4 + e] + lb[i * 4 + e];
;         if (write_x) *(float4*)(xr + i * 256 + lane * 4) = make_float4(v[i * 4 + 0], v[i * 4 + 1], v[i * 4 + 2], v[i * 4 + 3]);
;     ...
;     for (int ri = 0; ri < 32; ++ri) {
;       float v[16];
;       v[0] = nx0.x; v[1] = nx0.y; v[2] = nx0.z; v[3] = nx0.w; v[4] = nx1.x; v[5] = nx1.y; v[6] = nx1.z; v[7] = nx1.w;
;       v[8] = nx2.x; v[9] = nx2.y; v[10] = nx2.z; v[11] = nx2.w; v[12] = nx3.x; v[13] = nx3.y; v[14] = nx3.z; v[15] = nx3.w;
;       {
;         const float* sn = src0 + (size_t)(ri < 31 ? ri + 1 : 31) * 1024;
;         nx0 = *(const float4*)(sn + lane * 4); nx1 = *(const float4*)(sn + 256 + lane * 4);
;         nx2 = *(const float4*)(sn + 512 + lane * 4); nx3 = *(const float4*)(sn + 768 + lane * 4);
;       }
;       __builtin_amdgcn_sched_barrier(0);
;       process(row0 + ri, v, msh, msc);
.LBB0_914:
	s_addk_i32 s29, 0x400
	v_add_u32_e32 v110, 1, v110
	s_cmpk_eq_u32 s29, 0x8400
	s_waitcnt vmcnt(4)
	v_mov_b64_e32 v[74:75], v[70:71]
	v_mov_b64_e32 v[72:73], v[68:69]
	v_mov_b64_e32 v[86:87], v[66:67]
	v_mov_b64_e32 v[84:85], v[64:65]
	v_mov_b64_e32 v[82:83], v[58:59]
	v_mov_b64_e32 v[78:79], v[62:63]
	v_mov_b64_e32 v[76:77], v[60:61]
	v_mov_b64_e32 v[80:81], v[56:57]
	s_cbranch_scc1 .LBB0_909
.LBB0_915:
	s_cmpk_lg_u32 s29, 0x8000
	s_cselect_b32 s82, s29, 0x7c00
	v_lshl_add_u64 v[68:69], s[82:83], 2, v[108:109]
	global_load_dwordx4 v[56:59], v[68:69], off offset:2048
	global_load_dwordx4 v[64:67], v[68:69], off offset:3072
	global_load_dwordx4 v[60:63], v[68:69], off offset:1024
	s_nop 0
	global_load_dwordx4 v[68:71], v[68:69], off
	v_add_f32_e32 v114, 0, v72
	v_add_f32_e32 v114, v73, v114
	v_add_f32_e32 v114, v74, v114
	v_add_f32_e32 v114, v75, v114
	v_add_f32_e32 v114, v76, v114
	v_add_f32_e32 v114, v77, v114
	v_add_f32_e32 v114, v78, v114
	v_add_f32_e32 v114, v79, v114
	v_add_f32_e32 v114, v80, v114
	v_add_f32_e32 v114, v81, v114
	v_add_f32_e32 v114, v82, v114
	v_add_f32_e32 v114, v83, v114
	v_add_f32_e32 v114, v84, v114
	v_add_f32_e32 v114, v85, v114
	v_add_f32_e32 v114, v86, v114
	v_add_f32_e32 v114, v87, v114
	v_readlane_b32 s12, v253, 43
	v_readlane_b32 s13, v253, 44
	v_add_f32_dpp v114, v114, v114 quad_perm:[1,0,3,2] row_mask:0xf bank_mask:0xf bound_ctrl:1
	v_ashrrev_i32_e32 v111, 31, v110
	v_lshlrev_b64 v[112:113], 12, v[110:111]
	v_add_f32_dpp v114, v114, v114 quad_perm:[2,3,0,1] row_mask:0xf bank_mask:0xf bound_ctrl:1
	v_readlane_b32 s24, v253, 55
	v_readlane_b32 s25, v253, 56
	v_add_f32_dpp v114, v114, v114 row_half_mirror row_mask:0xf bank_mask:0xf bound_ctrl:1
	v_readlane_b32 s14, v253, 45
	v_lshl_add_u64 v[112:113], s[24:25], 0, v[112:113]
	v_add_f32_dpp v114, v114, v114 row_mirror row_mask:0xf bank_mask:0xf bound_ctrl:1
	v_readlane_b32 s15, v253, 46
	v_readlane_b32 s12, v114, 16
	v_readlane_b32 s13, v114, 48
	v_readlane_b32 s4, v114, 0
	v_readlane_b32 s5, v114, 32
	v_mov_b32_e32 v114, s12
	v_mov_b32_e32 v115, s13
	v_pk_add_f32 v[114:115], s[4:5], v[114:115]
	v_readlane_b32 s16, v253, 47
	v_add_f32_e32 v114, v114, v115
	v_mul_f32_e32 v114, 0x3a800000, v114
	v_pk_add_f32 v[76:77], v[76:77], v[114:115] op_sel_hi:[1,0] neg_lo:[0,1] neg_hi:[0,1]
	v_pk_add_f32 v[78:79], v[78:79], v[114:115] op_sel_hi:[1,0] neg_lo:[0,1] neg_hi:[0,1]
	v_pk_mul_f32 v[116:117], v[76:77], v[76:77]
	v_pk_add_f32 v[80:81], v[80:81], v[114:115] op_sel_hi:[1,0] neg_lo:[0,1] neg_hi:[0,1]
	v_pk_add_f32 v[82:83], v[82:83], v[114:115] op_sel_hi:[1,0] neg_lo:[0,1] neg_hi:[0,1]
	v_pk_add_f32 v[84:85], v[84:85], v[114:115] op_sel_hi:[1,0] neg_lo:[0,1] neg_hi:[0,1]
	v_pk_add_f32 v[86:87], v[86:87], v[114:115] op_sel_hi:[1,0] neg_lo:[0,1] neg_hi:[0,1]
	v_pk_add_f32 v[74:75], v[74:75], v[114:115] op_sel_hi:[1,0] neg_lo:[0,1] neg_hi:[0,1]
	v_pk_add_f32 v[72:73], v[72:73], v[114:115] op_sel_hi:[1,0] neg_lo:[0,1] neg_hi:[0,1]
	v_readlane_b32 s17, v253, 48
	v_readlane_b32 s18, v253, 49
	v_readlane_b32 s19, v253, 50
	v_readlane_b32 s20, v253, 51
	v_readlane_b32 s21, v253, 52
	v_readlane_b32 s22, v253, 53
	v_readlane_b32 s23, v253, 54
	v_readlane_b32 s26, v253, 57
	v_readlane_b32 s27, v253, 58
	v_pk_mul_f32 v[122:123], v[78:79], v[78:79]
	v_pk_mul_f32 v[124:125], v[80:81], v[80:81]
	v_pk_mul_f32 v[126:127], v[82:83], v[82:83]
	v_pk_mul_f32 v[128:129], v[84:85], v[84:85]
	v_pk_mul_f32 v[130:131], v[86:87], v[86:87]
	v_pk_mul_f32 v[132:133], v[74:75], v[74:75]
	v_pk_mul_f32 v[134:135], v[72:73], v[72:73]
	s_nop 0
	v_add_f32_e32 v115, v134, v135
	v_add_f32_e32 v115, v132, v115
	v_add_f32_e32 v115, v133, v115
	v_add_f32_e32 v115, v116, v115
	v_add_f32_e32 v115, v117, v115
	v_add_f32_e32 v115, v122, v115
	v_add_f32_e32 v115, v123, v115
	v_add_f32_e32 v115, v124, v115
	v_add_f32_e32 v115, v125, v115
	v_add_f32_e32 v115, v126, v115
	v_add_f32_e32 v115, v127, v115
	v_add_f32_e32 v115, v128, v115
	v_add_f32_e32 v115, v129, v115
	v_add_f32_e32 v115, v130, v115
	v_add_f32_e32 v115, v131, v115
	s_nop 1
	v_add_f32_dpp v115, v115, v115 quad_perm:[1,0,3,2] row_mask:0xf bank_mask:0xf bound_ctrl:1
	s_nop 1
	v_add_f32_dpp v115, v115, v115 quad_perm:[2,3,0,1] row_mask:0xf bank_mask:0xf bound_ctrl:1
	s_nop 1
	v_add_f32_dpp v115, v115, v115 row_half_mirror row_mask:0xf bank_mask:0xf bound_ctrl:1
	s_nop 1
	v_add_f32_dpp v115, v115, v115 row_mirror row_mask:0xf bank_mask:0xf bound_ctrl:1
	s_nop 0
	v_readlane_b32 s12, v115, 16
	v_readlane_b32 s13, v115, 48
	v_readlane_b32 s4, v115, 0
	v_readlane_b32 s5, v115, 32
	v_mov_b32_e32 v116, s12
	v_mov_b32_e32 v117, s13
	v_pk_add_f32 v[116:117], s[4:5], v[116:117]
	s_nop 0
	v_add_f32_e32 v115, v116, v117
	v_fmamk_f32 v115, v115, 0x3a800000, v217
	v_mul_f32_e32 v116, 0x4b800000, v115
	v_cmp_gt_f32_e32 vcc, s60, v115
	s_nop 1
	v_cndmask_b32_e32 v115, v115, v116, vcc
	v_rsq_f32_e32 v115, v115
	s_nop 0
	v_mul_f32_e32 v116, 0x45800000, v115
	v_cndmask_b32_e32 v116, v115, v116, vcc
	v_pk_mul_f32 v[72:73], v[72:73], v[116:117] op_sel_hi:[1,0]
	v_pk_mul_f32 v[74:75], v[74:75], v[116:117] op_sel_hi:[1,0]
	v_cndmask_b32_e64 v115, 0, 1, s[88:89]
	v_pk_fma_f32 v[72:73], v[8:9], v[72:73], v[16:17]
	v_cmp_ne_u32_e64 s[4:5], 1, v115
	s_andn2_b64 vcc, exec, s[88:89]
	v_pk_fma_f32 v[74:75], v[10:11], v[74:75], v[18:19]
	s_cbranch_vccnz .LBB0_917
	v_lshl_add_u64 v[122:123], v[112:113], 0, v[178:179]
	global_store_dwordx4 v[122:123], v[72:75], off
